# in-proj sigmoid and SiLU epilogues regenerated with packed f32 ops (v_pk_add/v_pk_mul), no per-convert pads; on stacked v12
# baseline (speedup 1.0000x reference)
;     template <int ACT>
;     __device__ __forceinline__ void plain(const f32x4 (&acc)[2][2][4][2], int pm, int wr, int wc, int fr, int fq, bf16_t* dst, int ld, int col0) const {
;         const int colw = col0 + 32 * wc + 8 * fq;
;         f32x4 b[2][2];
; #pragma unroll
;         for (int bj = 0; bj < 2; ++bj)
; #pragma unroll
;             for (int n = 0; n < 2; ++n) b[bj][n] = (ACT == 2) ? *(const f32x4*)(bmerge + colw + bj * 128 + 4 * n) : (f32x4){0.f, 0.f, 0.f, 0.f};
; #pragma unroll
;         for (int ai = 0; ai < 2; ++ai)
; #pragma unroll
;             for (int m = 0; m < 4; ++m) {
;                 const size_t row = (size_t)pm * 256 + ai * 128 + wr * 64 + m * 16 + fr;
; #pragma unroll
;                 for (int bj = 0; bj < 2; ++bj) {
;                     f32x4 v0 = acc[ai][bj][m][0], v1 = acc[ai][bj][m][1];
;                     if (ACT == 1) { for (int j = 0; j < 4; ++j) { v0[j] = silu_f(v0[j]); v1[j] = silu_f(v1[j]); } }
;                     if (ACT == 2) { v0 = v0 + b[bj][0]; v1 = v1 + b[bj][1]; for (int j = 0; j < 4; ++j) { v0[j] = sigm_f(v0[j]); v1[j] = sigm_f(v1[j]); } }
;                     if (ACT == 0) store8(dst + row * ld + colw + bj * 128, v0, v1); else store8_safe(dst + row * ld + colw + bj * 128, v0, v1);
;                 }
;                 __builtin_amdgcn_sched_barrier(0);
;             }
;     __device__ __forceinline__ void operator()(const f32x4 (&acc)[2][2][4][2], const Unit& u, int wr, int wc, int fr, int fq, int wid) const {
;     ...
;         if (t < 4 && (MK_G1T & 1)) norm_rope_store<128>(acc, pm, wr, wc, fr, fq, wid, wAq, tc128, ts128, rope, one, QA, 1024, (t * 2 + (wc >> 1)) * 128, 1, 0, xch, 0.08838834764831845f * 1.4426950408889634f);
;         else if (t == 4 && (MK_G1T & 1)) norm_rope_store<128>(acc, pm, wr, wc, fr, fq, wid, wAk, tc128, ts128, rope, one, KA, 256, (wc >> 1) * 128, 1, 0, xch);
;         else if (t == 5 && (MK_G1T & 2)) plain<0>(acc, pm, wr, wc, fr, fq, VA, 256, 0);
;         else if (t < 10 && (MK_G1T & 1)) norm_rope_store<128>(acc, pm, wr, wc, fr, fq, wid, wBqn, tc128, ts128, false, one, QB, 1536, ((t - 6) * 2 + (wc >> 1)) * 192, 1, 0, xch, 0.07216878364870323f * 1.4426950408889634f);
;         else if (t < 12 && (MK_G1T & 4)) norm_rope_store<64>(acc, pm, wr, wc, fr, fq, wid, wBqr, tc64, ts64, rope, one, QB, 1536, ((t - 10) * 4 + wc) * 192 + 128, 1, 0, xch, 0.07216878364870323f * 1.4426950408889634f);
.LBB0_220:
	s_cmp_lt_i32 s36, 5
	s_cbranch_scc1 .LBB0_345
	s_cmp_lg_u32 s36, 5
	s_cbranch_scc0 .LBB0_342
	s_cmp_gt_u32 s36, 9
	s_cbranch_scc0 .LBB0_337
	s_cmp_gt_u32 s36, 11
	s_cbranch_scc0 .LBB0_317
	s_cmp_gt_u32 s36, 13
	s_cbranch_scc0 .LBB0_298
	s_cmp_lg_u32 s36, 14
	s_cbranch_scc0 .LBB0_277
	s_cmp_gt_u32 s36, 18
	s_cbranch_scc0 .LBB0_257
	s_cmp_gt_u32 s36, 22
	s_cbranch_scc0 .LBB0_237
	s_lshl_b32 s2, s36, 8
	s_cmp_gt_u32 s36, 26
	s_cbranch_scc0 .LBB0_234
	s_lshl_b32 s3, s90, 5
	s_cmp_gt_u32 s36, 38
	v_lshlrev_b32_e32 v146, 3, v237
	s_cbranch_scc0 .LBB0_231
	s_add_i32 s4, s2, s3
	s_addk_i32 s4, 0xd900
	v_add_u32_e32 v144, s4, v146
	v_readlane_b32 s4, v255, 4
	v_ashrrev_i32_e32 v145, 31, v144
	v_readlane_b32 s5, v255, 5
	s_ashr_i32 s31, s30, 31
	s_lshl_b32 s10, s13, 6
	v_lshl_add_u64 v[132:133], v[144:145], 2, s[4:5]
	global_load_dwordx4 v[136:139], v[132:133], off offset:16
	global_load_dwordx4 v[140:143], v[132:133], off
	global_load_dwordx4 v[128:131], v[132:133], off offset:528
	s_nop 0
	global_load_dwordx4 v[132:135], v[132:133], off offset:512
	s_lshl_b64 s[4:5], s[30:31], 8
	s_ashr_i32 s20, s10, 31
	s_add_u32 s4, s10, s4
	v_ashrrev_i32_e32 v205, 31, v204
	s_addc_u32 s5, s20, s5
	v_lshl_add_u64 v[148:149], s[4:5], 0, v[204:205]
	v_lshl_add_u64 v[144:145], v[144:145], 1, s[38:39]
	v_mad_u64_u32 v[144:145], s[4:5], v148, s40, v[144:145]
	v_mad_i32_i24 v145, v149, s40, v145
	s_waitcnt vmcnt(0)
	s_mov_b32 s4, 0xbfb8aa3b
	s_mov_b32 s5, 0xbfb8aa3b
	v_pk_add_f32 v[152:153], v[108:109], v[136:137]
	v_pk_add_f32 v[154:155], v[110:111], v[138:139]
	v_pk_add_f32 v[148:149], v[124:125], v[140:141]
	v_pk_add_f32 v[150:151], v[126:127], v[142:143]
	v_pk_mul_f32 v[152:153], v[152:153], s[4:5]
	v_pk_mul_f32 v[154:155], v[154:155], s[4:5]
	v_pk_mul_f32 v[148:149], v[148:149], s[4:5]
	v_pk_mul_f32 v[150:151], v[150:151], s[4:5]
	v_exp_f32_e32 v152, v152
	v_exp_f32_e32 v153, v153
	v_exp_f32_e32 v154, v154
	v_exp_f32_e32 v155, v155
	v_exp_f32_e32 v148, v148
	v_exp_f32_e32 v149, v149
	v_exp_f32_e32 v150, v150
	v_exp_f32_e32 v151, v151
	v_pk_add_f32 v[152:153], v[152:153], 1.0 op_sel_hi:[1,0]
	v_pk_add_f32 v[154:155], v[154:155], 1.0 op_sel_hi:[1,0]
	v_pk_add_f32 v[148:149], v[148:149], 1.0 op_sel_hi:[1,0]
	v_pk_add_f32 v[150:151], v[150:151], 1.0 op_sel_hi:[1,0]
	v_rcp_f32_e32 v152, v152
	v_rcp_f32_e32 v153, v153
	v_rcp_f32_e32 v154, v154
	v_rcp_f32_e32 v155, v155
	v_rcp_f32_e32 v148, v148
	v_rcp_f32_e32 v149, v149
	v_rcp_f32_e32 v150, v150
	v_rcp_f32_e32 v151, v151
	v_cvt_pk_bf16_f32 v148, v148, v149
	v_cvt_pk_bf16_f32 v149, v150, v151
	v_cvt_pk_bf16_f32 v150, v152, v153
	v_cvt_pk_bf16_f32 v151, v154, v155
	global_store_dwordx4 v[144:145], v[148:151], off
	v_pk_add_f32 v[152:153], v[104:105], v[128:129]
	v_pk_add_f32 v[154:155], v[106:107], v[130:131]
	v_pk_add_f32 v[148:149], v[120:121], v[132:133]
	v_pk_add_f32 v[150:151], v[122:123], v[134:135]
	v_pk_mul_f32 v[152:153], v[152:153], s[4:5]
	v_pk_mul_f32 v[154:155], v[154:155], s[4:5]
	v_pk_mul_f32 v[148:149], v[148:149], s[4:5]
	v_pk_mul_f32 v[150:151], v[150:151], s[4:5]
	v_exp_f32_e32 v152, v152
	v_exp_f32_e32 v153, v153
	v_exp_f32_e32 v154, v154
	v_exp_f32_e32 v155, v155
	v_exp_f32_e32 v148, v148
	v_exp_f32_e32 v149, v149
	v_exp_f32_e32 v150, v150
	v_exp_f32_e32 v151, v151
	v_pk_add_f32 v[152:153], v[152:153], 1.0 op_sel_hi:[1,0]
	v_pk_add_f32 v[154:155], v[154:155], 1.0 op_sel_hi:[1,0]
	v_pk_add_f32 v[148:149], v[148:149], 1.0 op_sel_hi:[1,0]
	v_pk_add_f32 v[150:151], v[150:151], 1.0 op_sel_hi:[1,0]
	v_rcp_f32_e32 v152, v152
	v_rcp_f32_e32 v153, v153
	v_rcp_f32_e32 v154, v154
	v_rcp_f32_e32 v155, v155
	v_rcp_f32_e32 v148, v148
	v_rcp_f32_e32 v149, v149
	v_rcp_f32_e32 v150, v150
	v_rcp_f32_e32 v151, v151
	v_cvt_pk_bf16_f32 v148, v148, v149
	v_cvt_pk_bf16_f32 v149, v150, v151
	v_cvt_pk_bf16_f32 v150, v152, v153
	v_cvt_pk_bf16_f32 v151, v154, v155
	global_store_dwordx4 v[144:145], v[148:151], off offset:256
	v_add_co_u32_e32 v156, vcc, 0x30000, v144
	s_nop 1
	v_addc_co_u32_e32 v157, vcc, 0, v145, vcc
	v_pk_add_f32 v[152:153], v[100:101], v[136:137]
	v_pk_add_f32 v[154:155], v[102:103], v[138:139]
	v_pk_add_f32 v[148:149], v[116:117], v[140:141]
	v_pk_add_f32 v[150:151], v[118:119], v[142:143]
	v_pk_mul_f32 v[152:153], v[152:153], s[4:5]
	v_pk_mul_f32 v[154:155], v[154:155], s[4:5]
	v_pk_mul_f32 v[148:149], v[148:149], s[4:5]
	v_pk_mul_f32 v[150:151], v[150:151], s[4:5]
	v_exp_f32_e32 v152, v152
	v_exp_f32_e32 v153, v153
	v_exp_f32_e32 v154, v154
	v_exp_f32_e32 v155, v155
	v_exp_f32_e32 v148, v148
	v_exp_f32_e32 v149, v149
	v_exp_f32_e32 v150, v150
	v_exp_f32_e32 v151, v151
	v_pk_add_f32 v[152:153], v[152:153], 1.0 op_sel_hi:[1,0]
	v_pk_add_f32 v[154:155], v[154:155], 1.0 op_sel_hi:[1,0]
	v_pk_add_f32 v[148:149], v[148:149], 1.0 op_sel_hi:[1,0]
	v_pk_add_f32 v[150:151], v[150:151], 1.0 op_sel_hi:[1,0]
	v_rcp_f32_e32 v152, v152
	v_rcp_f32_e32 v153, v153
	v_rcp_f32_e32 v154, v154
	v_rcp_f32_e32 v155, v155
	v_rcp_f32_e32 v148, v148
	v_rcp_f32_e32 v149, v149
	v_rcp_f32_e32 v150, v150
	v_rcp_f32_e32 v151, v151
	v_cvt_pk_bf16_f32 v148, v148, v149
	v_cvt_pk_bf16_f32 v149, v150, v151
	v_cvt_pk_bf16_f32 v150, v152, v153
	v_cvt_pk_bf16_f32 v151, v154, v155
	global_store_dwordx4 v[156:157], v[148:151], off
	v_pk_add_f32 v[152:153], v[96:97], v[128:129]
	v_pk_add_f32 v[154:155], v[98:99], v[130:131]
	v_pk_add_f32 v[148:149], v[112:113], v[132:133]
	v_pk_add_f32 v[150:151], v[114:115], v[134:135]
	v_pk_mul_f32 v[152:153], v[152:153], s[4:5]
	v_pk_mul_f32 v[154:155], v[154:155], s[4:5]
	v_pk_mul_f32 v[148:149], v[148:149], s[4:5]
	v_pk_mul_f32 v[150:151], v[150:151], s[4:5]
	v_exp_f32_e32 v152, v152
; __device__ __forceinline__ float sigm_f(float x) { return __builtin_amdgcn_rcpf(1.f + __builtin_amdgcn_exp2f(-1.4426950408889634f * x)); }
; __device__ __forceinline__ float silu_f(float x) { return x * sigm_f(x); }
;     template <int ACT>
;     __device__ __forceinline__ void plain(const f32x4 (&acc)[2][2][4][2], int pm, int wr, int wc, int fr, int fq, bf16_t* dst, int ld, int col0) const {
;     ...
;         for (int ai = 0; ai < 2; ++ai)
; #pragma unroll
;             for (int m = 0; m < 4; ++m) {
;                 const size_t row = (size_t)pm * 256 + ai * 128 + wr * 64 + m * 16 + fr;
; #pragma unroll
;                 for (int bj = 0; bj < 2; ++bj) {
;                     f32x4 v0 = acc[ai][bj][m][0], v1 = acc[ai][bj][m][1];
;                     if (ACT == 1) { for (int j = 0; j < 4; ++j) { v0[j] = silu_f(v0[j]); v1[j] = silu_f(v1[j]); } }
;                     if (ACT == 2) { v0 = v0 + b[bj][0]; v1 = v1 + b[bj][1]; for (int j = 0; j < 4; ++j) { v0[j] = sigm_f(v0[j]); v1[j] = sigm_f(v1[j]); } }
;                     if (ACT == 0) store8(dst + row * ld + colw + bj * 128, v0, v1); else store8_safe(dst + row * ld + colw + bj * 128, v0, v1);
;                 }
;                 __builtin_amdgcn_sched_barrier(0);
;             }
	v_exp_f32_e32 v153, v153
	v_exp_f32_e32 v154, v154
	v_exp_f32_e32 v155, v155
	v_exp_f32_e32 v148, v148
	v_exp_f32_e32 v149, v149
	v_exp_f32_e32 v150, v150
	v_exp_f32_e32 v151, v151
	v_pk_add_f32 v[152:153], v[152:153], 1.0 op_sel_hi:[1,0]
	v_pk_add_f32 v[154:155], v[154:155], 1.0 op_sel_hi:[1,0]
	v_pk_add_f32 v[148:149], v[148:149], 1.0 op_sel_hi:[1,0]
	v_pk_add_f32 v[150:151], v[150:151], 1.0 op_sel_hi:[1,0]
	v_rcp_f32_e32 v152, v152
	v_rcp_f32_e32 v153, v153
	v_rcp_f32_e32 v154, v154
	v_rcp_f32_e32 v155, v155
	v_rcp_f32_e32 v148, v148
	v_rcp_f32_e32 v149, v149
	v_rcp_f32_e32 v150, v150
	v_rcp_f32_e32 v151, v151
	v_cvt_pk_bf16_f32 v148, v148, v149
	v_cvt_pk_bf16_f32 v149, v150, v151
	v_cvt_pk_bf16_f32 v150, v152, v153
	v_cvt_pk_bf16_f32 v151, v154, v155
	global_store_dwordx4 v[156:157], v[148:151], off offset:256
	v_add_co_u32_e32 v156, vcc, 0x60000, v144
	s_nop 1
	v_addc_co_u32_e32 v157, vcc, 0, v145, vcc
	v_pk_add_f32 v[152:153], v[76:77], v[136:137]
	v_pk_add_f32 v[154:155], v[78:79], v[138:139]
	v_pk_add_f32 v[148:149], v[92:93], v[140:141]
	v_pk_add_f32 v[150:151], v[94:95], v[142:143]
	v_pk_mul_f32 v[152:153], v[152:153], s[4:5]
	v_pk_mul_f32 v[154:155], v[154:155], s[4:5]
	v_pk_mul_f32 v[148:149], v[148:149], s[4:5]
	v_pk_mul_f32 v[150:151], v[150:151], s[4:5]
	v_exp_f32_e32 v152, v152
	v_exp_f32_e32 v153, v153
	v_exp_f32_e32 v154, v154
	v_exp_f32_e32 v155, v155
	v_exp_f32_e32 v148, v148
	v_exp_f32_e32 v149, v149
	v_exp_f32_e32 v150, v150
	v_exp_f32_e32 v151, v151
	v_pk_add_f32 v[152:153], v[152:153], 1.0 op_sel_hi:[1,0]
	v_pk_add_f32 v[154:155], v[154:155], 1.0 op_sel_hi:[1,0]
	v_pk_add_f32 v[148:149], v[148:149], 1.0 op_sel_hi:[1,0]
	v_pk_add_f32 v[150:151], v[150:151], 1.0 op_sel_hi:[1,0]
	v_rcp_f32_e32 v152, v152
	v_rcp_f32_e32 v153, v153
	v_rcp_f32_e32 v154, v154
	v_rcp_f32_e32 v155, v155
	v_rcp_f32_e32 v148, v148
	v_rcp_f32_e32 v149, v149
	v_rcp_f32_e32 v150, v150
	v_rcp_f32_e32 v151, v151
	v_cvt_pk_bf16_f32 v148, v148, v149
	v_cvt_pk_bf16_f32 v149, v150, v151
	v_cvt_pk_bf16_f32 v150, v152, v153
	v_cvt_pk_bf16_f32 v151, v154, v155
	global_store_dwordx4 v[156:157], v[148:151], off
	v_pk_add_f32 v[152:153], v[72:73], v[128:129]
	v_pk_add_f32 v[154:155], v[74:75], v[130:131]
	v_pk_add_f32 v[148:149], v[88:89], v[132:133]
	v_pk_add_f32 v[150:151], v[90:91], v[134:135]
	v_pk_mul_f32 v[152:153], v[152:153], s[4:5]
	v_pk_mul_f32 v[154:155], v[154:155], s[4:5]
	v_pk_mul_f32 v[148:149], v[148:149], s[4:5]
	v_pk_mul_f32 v[150:151], v[150:151], s[4:5]
	v_exp_f32_e32 v152, v152
	v_exp_f32_e32 v153, v153
	v_exp_f32_e32 v154, v154
	v_exp_f32_e32 v155, v155
	v_exp_f32_e32 v148, v148
	v_exp_f32_e32 v149, v149
	v_exp_f32_e32 v150, v150
	v_exp_f32_e32 v151, v151
	v_pk_add_f32 v[152:153], v[152:153], 1.0 op_sel_hi:[1,0]
	v_pk_add_f32 v[154:155], v[154:155], 1.0 op_sel_hi:[1,0]
	v_pk_add_f32 v[148:149], v[148:149], 1.0 op_sel_hi:[1,0]
	v_pk_add_f32 v[150:151], v[150:151], 1.0 op_sel_hi:[1,0]
	v_rcp_f32_e32 v152, v152
	v_rcp_f32_e32 v153, v153
	v_rcp_f32_e32 v154, v154
	v_rcp_f32_e32 v155, v155
	v_rcp_f32_e32 v148, v148
	v_rcp_f32_e32 v149, v149
	v_rcp_f32_e32 v150, v150
	v_rcp_f32_e32 v151, v151
	v_cvt_pk_bf16_f32 v148, v148, v149
	v_cvt_pk_bf16_f32 v149, v150, v151
	v_cvt_pk_bf16_f32 v150, v152, v153
	v_cvt_pk_bf16_f32 v151, v154, v155
	global_store_dwordx4 v[156:157], v[148:151], off offset:256
	v_add_co_u32_e32 v156, vcc, 0x90000, v144
	s_nop 1
	v_addc_co_u32_e32 v157, vcc, 0, v145, vcc
	v_pk_add_f32 v[152:153], v[68:69], v[136:137]
	v_pk_add_f32 v[154:155], v[70:71], v[138:139]
	v_pk_add_f32 v[148:149], v[84:85], v[140:141]
	v_pk_add_f32 v[150:151], v[86:87], v[142:143]
	v_pk_mul_f32 v[152:153], v[152:153], s[4:5]
	v_pk_mul_f32 v[154:155], v[154:155], s[4:5]
	v_pk_mul_f32 v[148:149], v[148:149], s[4:5]
	v_pk_mul_f32 v[150:151], v[150:151], s[4:5]
	v_exp_f32_e32 v152, v152
	v_exp_f32_e32 v153, v153
	v_exp_f32_e32 v154, v154
	v_exp_f32_e32 v155, v155
	v_exp_f32_e32 v148, v148
	v_exp_f32_e32 v149, v149
	v_exp_f32_e32 v150, v150
	v_exp_f32_e32 v151, v151
	v_pk_add_f32 v[152:153], v[152:153], 1.0 op_sel_hi:[1,0]
	v_pk_add_f32 v[154:155], v[154:155], 1.0 op_sel_hi:[1,0]
	v_pk_add_f32 v[148:149], v[148:149], 1.0 op_sel_hi:[1,0]
	v_pk_add_f32 v[150:151], v[150:151], 1.0 op_sel_hi:[1,0]
	v_rcp_f32_e32 v152, v152
	v_rcp_f32_e32 v153, v153
	v_rcp_f32_e32 v154, v154
	v_rcp_f32_e32 v155, v155
	v_rcp_f32_e32 v148, v148
	v_rcp_f32_e32 v149, v149
	v_rcp_f32_e32 v150, v150
	v_rcp_f32_e32 v151, v151
	v_cvt_pk_bf16_f32 v148, v148, v149
	v_cvt_pk_bf16_f32 v149, v150, v151
	v_cvt_pk_bf16_f32 v150, v152, v153
	v_cvt_pk_bf16_f32 v151, v154, v155
	global_store_dwordx4 v[156:157], v[148:151], off
	v_pk_add_f32 v[152:153], v[64:65], v[128:129]
	v_pk_add_f32 v[154:155], v[66:67], v[130:131]
	v_pk_add_f32 v[148:149], v[80:81], v[132:133]
	v_pk_add_f32 v[150:151], v[82:83], v[134:135]
	v_pk_mul_f32 v[152:153], v[152:153], s[4:5]
	v_pk_mul_f32 v[154:155], v[154:155], s[4:5]
	v_pk_mul_f32 v[148:149], v[148:149], s[4:5]
	v_pk_mul_f32 v[150:151], v[150:151], s[4:5]
	v_exp_f32_e32 v152, v152
	v_exp_f32_e32 v153, v153
	v_exp_f32_e32 v154, v154
	v_exp_f32_e32 v155, v155
	v_exp_f32_e32 v148, v148
	v_exp_f32_e32 v149, v149
	v_exp_f32_e32 v150, v150
	v_exp_f32_e32 v151, v151
	v_pk_add_f32 v[152:153], v[152:153], 1.0 op_sel_hi:[1,0]
	v_pk_add_f32 v[154:155], v[154:155], 1.0 op_sel_hi:[1,0]
	v_pk_add_f32 v[148:149], v[148:149], 1.0 op_sel_hi:[1,0]
	v_pk_add_f32 v[150:151], v[150:151], 1.0 op_sel_hi:[1,0]
	v_rcp_f32_e32 v152, v152
	v_rcp_f32_e32 v153, v153
	v_rcp_f32_e32 v154, v154
	v_rcp_f32_e32 v155, v155
	v_rcp_f32_e32 v148, v148
	v_rcp_f32_e32 v149, v149
	v_rcp_f32_e32 v150, v150
; __device__ __forceinline__ float sigm_f(float x) { return __builtin_amdgcn_rcpf(1.f + __builtin_amdgcn_exp2f(-1.4426950408889634f * x)); }
; __device__ __forceinline__ float silu_f(float x) { return x * sigm_f(x); }
;     template <int ACT>
;     __device__ __forceinline__ void plain(const f32x4 (&acc)[2][2][4][2], int pm, int wr, int wc, int fr, int fq, bf16_t* dst, int ld, int col0) const {
;     ...
;         for (int ai = 0; ai < 2; ++ai)
; #pragma unroll
;             for (int m = 0; m < 4; ++m) {
;                 const size_t row = (size_t)pm * 256 + ai * 128 + wr * 64 + m * 16 + fr;
; #pragma unroll
;                 for (int bj = 0; bj < 2; ++bj) {
;                     f32x4 v0 = acc[ai][bj][m][0], v1 = acc[ai][bj][m][1];
;                     if (ACT == 1) { for (int j = 0; j < 4; ++j) { v0[j] = silu_f(v0[j]); v1[j] = silu_f(v1[j]); } }
;                     if (ACT == 2) { v0 = v0 + b[bj][0]; v1 = v1 + b[bj][1]; for (int j = 0; j < 4; ++j) { v0[j] = sigm_f(v0[j]); v1[j] = sigm_f(v1[j]); } }
;                     if (ACT == 0) store8(dst + row * ld + colw + bj * 128, v0, v1); else store8_safe(dst + row * ld + colw + bj * 128, v0, v1);
;                 }
;                 __builtin_amdgcn_sched_barrier(0);
;             }
	v_rcp_f32_e32 v151, v151
	v_cvt_pk_bf16_f32 v148, v148, v149
	v_cvt_pk_bf16_f32 v149, v150, v151
	v_cvt_pk_bf16_f32 v150, v152, v153
	v_cvt_pk_bf16_f32 v151, v154, v155
	global_store_dwordx4 v[156:157], v[148:151], off offset:256
	v_add_co_u32_e32 v156, vcc, 0x180000, v144
	s_nop 1
	v_addc_co_u32_e32 v157, vcc, 0, v145, vcc
	v_pk_add_f32 v[152:153], v[44:45], v[136:137]
	v_pk_add_f32 v[154:155], v[46:47], v[138:139]
	v_pk_add_f32 v[148:149], v[60:61], v[140:141]
	v_pk_add_f32 v[150:151], v[62:63], v[142:143]
	v_pk_mul_f32 v[152:153], v[152:153], s[4:5]
	v_pk_mul_f32 v[154:155], v[154:155], s[4:5]
	v_pk_mul_f32 v[148:149], v[148:149], s[4:5]
	v_pk_mul_f32 v[150:151], v[150:151], s[4:5]
	v_exp_f32_e32 v152, v152
	v_exp_f32_e32 v153, v153
	v_exp_f32_e32 v154, v154
	v_exp_f32_e32 v155, v155
	v_exp_f32_e32 v148, v148
	v_exp_f32_e32 v149, v149
	v_exp_f32_e32 v150, v150
	v_exp_f32_e32 v151, v151
	v_pk_add_f32 v[152:153], v[152:153], 1.0 op_sel_hi:[1,0]
	v_pk_add_f32 v[154:155], v[154:155], 1.0 op_sel_hi:[1,0]
	v_pk_add_f32 v[148:149], v[148:149], 1.0 op_sel_hi:[1,0]
	v_pk_add_f32 v[150:151], v[150:151], 1.0 op_sel_hi:[1,0]
	v_rcp_f32_e32 v152, v152
	v_rcp_f32_e32 v153, v153
	v_rcp_f32_e32 v154, v154
	v_rcp_f32_e32 v155, v155
	v_rcp_f32_e32 v148, v148
	v_rcp_f32_e32 v149, v149
	v_rcp_f32_e32 v150, v150
	v_rcp_f32_e32 v151, v151
	v_cvt_pk_bf16_f32 v148, v148, v149
	v_cvt_pk_bf16_f32 v149, v150, v151
	v_cvt_pk_bf16_f32 v150, v152, v153
	v_cvt_pk_bf16_f32 v151, v154, v155
	global_store_dwordx4 v[156:157], v[148:151], off
	v_pk_add_f32 v[152:153], v[40:41], v[128:129]
	v_pk_add_f32 v[154:155], v[42:43], v[130:131]
	v_pk_add_f32 v[148:149], v[56:57], v[132:133]
	v_pk_add_f32 v[150:151], v[58:59], v[134:135]
	v_pk_mul_f32 v[152:153], v[152:153], s[4:5]
	v_pk_mul_f32 v[154:155], v[154:155], s[4:5]
	v_pk_mul_f32 v[148:149], v[148:149], s[4:5]
	v_pk_mul_f32 v[150:151], v[150:151], s[4:5]
	v_exp_f32_e32 v152, v152
	v_exp_f32_e32 v153, v153
	v_exp_f32_e32 v154, v154
	v_exp_f32_e32 v155, v155
	v_exp_f32_e32 v148, v148
	v_exp_f32_e32 v149, v149
	v_exp_f32_e32 v150, v150
	v_exp_f32_e32 v151, v151
	v_pk_add_f32 v[152:153], v[152:153], 1.0 op_sel_hi:[1,0]
	v_pk_add_f32 v[154:155], v[154:155], 1.0 op_sel_hi:[1,0]
	v_pk_add_f32 v[148:149], v[148:149], 1.0 op_sel_hi:[1,0]
	v_pk_add_f32 v[150:151], v[150:151], 1.0 op_sel_hi:[1,0]
	v_rcp_f32_e32 v152, v152
	v_rcp_f32_e32 v153, v153
	v_rcp_f32_e32 v154, v154
	v_rcp_f32_e32 v155, v155
	v_rcp_f32_e32 v148, v148
	v_rcp_f32_e32 v149, v149
	v_rcp_f32_e32 v150, v150
	v_rcp_f32_e32 v151, v151
	v_cvt_pk_bf16_f32 v148, v148, v149
	v_cvt_pk_bf16_f32 v149, v150, v151
	v_cvt_pk_bf16_f32 v150, v152, v153
	v_cvt_pk_bf16_f32 v151, v154, v155
	global_store_dwordx4 v[156:157], v[148:151], off offset:256
	v_add_co_u32_e32 v156, vcc, 0x1b0000, v144
	s_nop 1
	v_addc_co_u32_e32 v157, vcc, 0, v145, vcc
	v_pk_add_f32 v[152:153], v[36:37], v[136:137]
	v_pk_add_f32 v[154:155], v[38:39], v[138:139]
	v_pk_add_f32 v[148:149], v[52:53], v[140:141]
	v_pk_add_f32 v[150:151], v[54:55], v[142:143]
	v_pk_mul_f32 v[152:153], v[152:153], s[4:5]
	v_pk_mul_f32 v[154:155], v[154:155], s[4:5]
	v_pk_mul_f32 v[148:149], v[148:149], s[4:5]
	v_pk_mul_f32 v[150:151], v[150:151], s[4:5]
	v_exp_f32_e32 v152, v152
	v_exp_f32_e32 v153, v153
	v_exp_f32_e32 v154, v154
	v_exp_f32_e32 v155, v155
	v_exp_f32_e32 v148, v148
	v_exp_f32_e32 v149, v149
	v_exp_f32_e32 v150, v150
	v_exp_f32_e32 v151, v151
	v_pk_add_f32 v[152:153], v[152:153], 1.0 op_sel_hi:[1,0]
	v_pk_add_f32 v[154:155], v[154:155], 1.0 op_sel_hi:[1,0]
	v_pk_add_f32 v[148:149], v[148:149], 1.0 op_sel_hi:[1,0]
	v_pk_add_f32 v[150:151], v[150:151], 1.0 op_sel_hi:[1,0]
	v_rcp_f32_e32 v152, v152
	v_rcp_f32_e32 v153, v153
	v_rcp_f32_e32 v154, v154
	v_rcp_f32_e32 v155, v155
	v_rcp_f32_e32 v148, v148
	v_rcp_f32_e32 v149, v149
	v_rcp_f32_e32 v150, v150
	v_rcp_f32_e32 v151, v151
	v_cvt_pk_bf16_f32 v148, v148, v149
	v_cvt_pk_bf16_f32 v149, v150, v151
	v_cvt_pk_bf16_f32 v150, v152, v153
	v_cvt_pk_bf16_f32 v151, v154, v155
	global_store_dwordx4 v[156:157], v[148:151], off
	v_pk_add_f32 v[152:153], v[32:33], v[128:129]
	v_pk_add_f32 v[154:155], v[34:35], v[130:131]
	v_pk_add_f32 v[148:149], v[48:49], v[132:133]
	v_pk_add_f32 v[150:151], v[50:51], v[134:135]
	v_pk_mul_f32 v[152:153], v[152:153], s[4:5]
	v_pk_mul_f32 v[154:155], v[154:155], s[4:5]
	v_pk_mul_f32 v[148:149], v[148:149], s[4:5]
	v_pk_mul_f32 v[150:151], v[150:151], s[4:5]
	v_exp_f32_e32 v152, v152
	v_exp_f32_e32 v153, v153
	v_exp_f32_e32 v154, v154
	v_exp_f32_e32 v155, v155
	v_exp_f32_e32 v148, v148
	v_exp_f32_e32 v149, v149
	v_exp_f32_e32 v150, v150
	v_exp_f32_e32 v151, v151
	v_pk_add_f32 v[152:153], v[152:153], 1.0 op_sel_hi:[1,0]
	v_pk_add_f32 v[154:155], v[154:155], 1.0 op_sel_hi:[1,0]
	v_pk_add_f32 v[148:149], v[148:149], 1.0 op_sel_hi:[1,0]
	v_pk_add_f32 v[150:151], v[150:151], 1.0 op_sel_hi:[1,0]
	v_rcp_f32_e32 v152, v152
	v_rcp_f32_e32 v153, v153
	v_rcp_f32_e32 v154, v154
	v_rcp_f32_e32 v155, v155
	v_rcp_f32_e32 v148, v148
	v_rcp_f32_e32 v149, v149
	v_rcp_f32_e32 v150, v150
	v_rcp_f32_e32 v151, v151
	v_cvt_pk_bf16_f32 v148, v148, v149
	v_cvt_pk_bf16_f32 v149, v150, v151
	v_cvt_pk_bf16_f32 v150, v152, v153
	v_cvt_pk_bf16_f32 v151, v154, v155
	global_store_dwordx4 v[156:157], v[148:151], off offset:256
	v_add_co_u32_e32 v156, vcc, 0x1e0000, v144
	s_nop 1
	v_addc_co_u32_e32 v157, vcc, 0, v145, vcc
	v_pk_add_f32 v[152:153], v[12:13], v[136:137]
	v_pk_add_f32 v[154:155], v[14:15], v[138:139]
	v_pk_add_f32 v[148:149], v[28:29], v[140:141]
	v_pk_add_f32 v[150:151], v[30:31], v[142:143]
	v_pk_mul_f32 v[152:153], v[152:153], s[4:5]
	v_pk_mul_f32 v[154:155], v[154:155], s[4:5]
; __device__ __forceinline__ float sigm_f(float x) { return __builtin_amdgcn_rcpf(1.f + __builtin_amdgcn_exp2f(-1.4426950408889634f * x)); }
; __device__ __forceinline__ float silu_f(float x) { return x * sigm_f(x); }
;     template <int ACT>
;     __device__ __forceinline__ void plain(const f32x4 (&acc)[2][2][4][2], int pm, int wr, int wc, int fr, int fq, bf16_t* dst, int ld, int col0) const {
;     ...
;         for (int ai = 0; ai < 2; ++ai)
; #pragma unroll
;             for (int m = 0; m < 4; ++m) {
;                 const size_t row = (size_t)pm * 256 + ai * 128 + wr * 64 + m * 16 + fr;
; #pragma unroll
;                 for (int bj = 0; bj < 2; ++bj) {
;                     f32x4 v0 = acc[ai][bj][m][0], v1 = acc[ai][bj][m][1];
;                     if (ACT == 1) { for (int j = 0; j < 4; ++j) { v0[j] = silu_f(v0[j]); v1[j] = silu_f(v1[j]); } }
;                     if (ACT == 2) { v0 = v0 + b[bj][0]; v1 = v1 + b[bj][1]; for (int j = 0; j < 4; ++j) { v0[j] = sigm_f(v0[j]); v1[j] = sigm_f(v1[j]); } }
;                     if (ACT == 0) store8(dst + row * ld + colw + bj * 128, v0, v1); else store8_safe(dst + row * ld + colw + bj * 128, v0, v1);
;                 }
;                 __builtin_amdgcn_sched_barrier(0);
;             }
	v_pk_mul_f32 v[148:149], v[148:149], s[4:5]
	v_pk_mul_f32 v[150:151], v[150:151], s[4:5]
	v_exp_f32_e32 v152, v152
	v_exp_f32_e32 v153, v153
	v_exp_f32_e32 v154, v154
	v_exp_f32_e32 v155, v155
	v_exp_f32_e32 v148, v148
	v_exp_f32_e32 v149, v149
	v_exp_f32_e32 v150, v150
	v_exp_f32_e32 v151, v151
	v_pk_add_f32 v[152:153], v[152:153], 1.0 op_sel_hi:[1,0]
	v_pk_add_f32 v[154:155], v[154:155], 1.0 op_sel_hi:[1,0]
	v_pk_add_f32 v[148:149], v[148:149], 1.0 op_sel_hi:[1,0]
	v_pk_add_f32 v[150:151], v[150:151], 1.0 op_sel_hi:[1,0]
	v_rcp_f32_e32 v152, v152
	v_rcp_f32_e32 v153, v153
	v_rcp_f32_e32 v154, v154
	v_rcp_f32_e32 v155, v155
	v_rcp_f32_e32 v148, v148
	v_rcp_f32_e32 v149, v149
	v_rcp_f32_e32 v150, v150
	v_rcp_f32_e32 v151, v151
	v_cvt_pk_bf16_f32 v148, v148, v149
	v_cvt_pk_bf16_f32 v149, v150, v151
	v_cvt_pk_bf16_f32 v150, v152, v153
	v_cvt_pk_bf16_f32 v151, v154, v155
	global_store_dwordx4 v[156:157], v[148:151], off
	v_pk_add_f32 v[152:153], v[8:9], v[128:129]
	v_pk_add_f32 v[154:155], v[10:11], v[130:131]
	v_pk_add_f32 v[148:149], v[24:25], v[132:133]
	v_pk_add_f32 v[150:151], v[26:27], v[134:135]
	v_pk_mul_f32 v[152:153], v[152:153], s[4:5]
	v_pk_mul_f32 v[154:155], v[154:155], s[4:5]
	v_pk_mul_f32 v[148:149], v[148:149], s[4:5]
	v_pk_mul_f32 v[150:151], v[150:151], s[4:5]
	v_exp_f32_e32 v152, v152
	v_exp_f32_e32 v153, v153
	v_exp_f32_e32 v154, v154
	v_exp_f32_e32 v155, v155
	v_exp_f32_e32 v148, v148
	v_exp_f32_e32 v149, v149
	v_exp_f32_e32 v150, v150
	v_exp_f32_e32 v151, v151
	v_pk_add_f32 v[152:153], v[152:153], 1.0 op_sel_hi:[1,0]
	v_pk_add_f32 v[154:155], v[154:155], 1.0 op_sel_hi:[1,0]
	v_pk_add_f32 v[148:149], v[148:149], 1.0 op_sel_hi:[1,0]
	v_pk_add_f32 v[150:151], v[150:151], 1.0 op_sel_hi:[1,0]
	v_rcp_f32_e32 v152, v152
	v_rcp_f32_e32 v153, v153
	v_rcp_f32_e32 v154, v154
	v_rcp_f32_e32 v155, v155
	v_rcp_f32_e32 v148, v148
	v_rcp_f32_e32 v149, v149
	v_rcp_f32_e32 v150, v150
	v_rcp_f32_e32 v151, v151
	v_cvt_pk_bf16_f32 v148, v148, v149
	v_cvt_pk_bf16_f32 v149, v150, v151
	v_cvt_pk_bf16_f32 v150, v152, v153
	v_cvt_pk_bf16_f32 v151, v154, v155
	global_store_dwordx4 v[156:157], v[148:151], off offset:256
	v_add_co_u32_e32 v156, vcc, 0x210000, v144
	s_nop 1
	v_addc_co_u32_e32 v157, vcc, 0, v145, vcc
	v_pk_add_f32 v[152:153], v[4:5], v[136:137]
	v_pk_add_f32 v[154:155], v[6:7], v[138:139]
	v_pk_add_f32 v[148:149], v[20:21], v[140:141]
	v_pk_add_f32 v[150:151], v[22:23], v[142:143]
	v_pk_mul_f32 v[152:153], v[152:153], s[4:5]
	v_pk_mul_f32 v[154:155], v[154:155], s[4:5]
	v_pk_mul_f32 v[148:149], v[148:149], s[4:5]
	v_pk_mul_f32 v[150:151], v[150:151], s[4:5]
	v_exp_f32_e32 v152, v152
	v_exp_f32_e32 v153, v153
	v_exp_f32_e32 v154, v154
	v_exp_f32_e32 v155, v155
	v_exp_f32_e32 v148, v148
	v_exp_f32_e32 v149, v149
	v_exp_f32_e32 v150, v150
	v_exp_f32_e32 v151, v151
	v_pk_add_f32 v[152:153], v[152:153], 1.0 op_sel_hi:[1,0]
	v_pk_add_f32 v[154:155], v[154:155], 1.0 op_sel_hi:[1,0]
	v_pk_add_f32 v[148:149], v[148:149], 1.0 op_sel_hi:[1,0]
	v_pk_add_f32 v[150:151], v[150:151], 1.0 op_sel_hi:[1,0]
	v_rcp_f32_e32 v152, v152
	v_rcp_f32_e32 v153, v153
	v_rcp_f32_e32 v154, v154
	v_rcp_f32_e32 v155, v155
	v_rcp_f32_e32 v148, v148
	v_rcp_f32_e32 v149, v149
	v_rcp_f32_e32 v150, v150
	v_rcp_f32_e32 v151, v151
	v_cvt_pk_bf16_f32 v148, v148, v149
	v_cvt_pk_bf16_f32 v149, v150, v151
	v_cvt_pk_bf16_f32 v150, v152, v153
	v_cvt_pk_bf16_f32 v151, v154, v155
	global_store_dwordx4 v[156:157], v[148:151], off
	v_pk_add_f32 v[152:153], v[0:1], v[128:129]
	v_pk_add_f32 v[154:155], v[2:3], v[130:131]
	v_pk_add_f32 v[148:149], v[16:17], v[132:133]
	v_pk_add_f32 v[150:151], v[18:19], v[134:135]
	v_pk_mul_f32 v[152:153], v[152:153], s[4:5]
	v_pk_mul_f32 v[154:155], v[154:155], s[4:5]
	v_pk_mul_f32 v[148:149], v[148:149], s[4:5]
	v_pk_mul_f32 v[150:151], v[150:151], s[4:5]
	v_exp_f32_e32 v152, v152
	v_exp_f32_e32 v153, v153
	v_exp_f32_e32 v154, v154
	v_exp_f32_e32 v155, v155
	v_exp_f32_e32 v148, v148
	v_exp_f32_e32 v149, v149
	v_exp_f32_e32 v150, v150
	v_exp_f32_e32 v151, v151
	v_pk_add_f32 v[152:153], v[152:153], 1.0 op_sel_hi:[1,0]
	v_pk_add_f32 v[154:155], v[154:155], 1.0 op_sel_hi:[1,0]
	v_pk_add_f32 v[148:149], v[148:149], 1.0 op_sel_hi:[1,0]
	v_pk_add_f32 v[150:151], v[150:151], 1.0 op_sel_hi:[1,0]
	v_rcp_f32_e32 v152, v152
	v_rcp_f32_e32 v153, v153
	v_rcp_f32_e32 v154, v154
	v_rcp_f32_e32 v155, v155
	v_rcp_f32_e32 v148, v148
	v_rcp_f32_e32 v149, v149
	v_rcp_f32_e32 v150, v150
	v_rcp_f32_e32 v151, v151
	v_cvt_pk_bf16_f32 v148, v148, v149
	v_cvt_pk_bf16_f32 v149, v150, v151
	v_cvt_pk_bf16_f32 v150, v152, v153
	v_cvt_pk_bf16_f32 v151, v154, v155
	global_store_dwordx4 v[156:157], v[148:151], off offset:256
	s_mov_b64 s[46:47], 0
; __device__ __forceinline__ float sigm_f(float x) { return __builtin_amdgcn_rcpf(1.f + __builtin_amdgcn_exp2f(-1.4426950408889634f * x)); }
; __device__ __forceinline__ float silu_f(float x) { return x * sigm_f(x); }
;     template <int ACT>
;     __device__ __forceinline__ void plain(const f32x4 (&acc)[2][2][4][2], int pm, int wr, int wc, int fr, int fq, bf16_t* dst, int ld, int col0) const {
;         const int colw = col0 + 32 * wc + 8 * fq;
;         f32x4 b[2][2];
; #pragma unroll
;         for (int bj = 0; bj < 2; ++bj)
; #pragma unroll
;             for (int n = 0; n < 2; ++n) b[bj][n] = (ACT == 2) ? *(const f32x4*)(bmerge + colw + bj * 128 + 4 * n) : (f32x4){0.f, 0.f, 0.f, 0.f};
; #pragma unroll
;         for (int ai = 0; ai < 2; ++ai)
; #pragma unroll
;             for (int m = 0; m < 4; ++m) {
;                 const size_t row = (size_t)pm * 256 + ai * 128 + wr * 64 + m * 16 + fr;
; #pragma unroll
;                 for (int bj = 0; bj < 2; ++bj) {
;                     f32x4 v0 = acc[ai][bj][m][0], v1 = acc[ai][bj][m][1];
;                     if (ACT == 1) { for (int j = 0; j < 4; ++j) { v0[j] = silu_f(v0[j]); v1[j] = silu_f(v1[j]); } }
;                     if (ACT == 2) { v0 = v0 + b[bj][0]; v1 = v1 + b[bj][1]; for (int j = 0; j < 4; ++j) { v0[j] = sigm_f(v0[j]); v1[j] = sigm_f(v1[j]); } }
;                     if (ACT == 0) store8(dst + row * ld + colw + bj * 128, v0, v1); else store8_safe(dst + row * ld + colw + bj * 128, v0, v1);
;                 }
;                 __builtin_amdgcn_sched_barrier(0);
;             }
;     __device__ __forceinline__ void operator()(const f32x4 (&acc)[2][2][4][2], const Unit& u, int wr, int wc, int fr, int fq, int wid) const {
;     ...
;         else if (t < 39 && (MK_G1T & 32)) plain<1>(acc, pm, wr, wc, fr, fq, GATE, 3072, (t - 27) * 256);
.LBB0_231:
	s_andn2_b64 vcc, exec, s[46:47]
	s_cbranch_vccnz .LBB0_233
	s_add_i32 s3, s2, s3
	s_addk_i32 s3, 0xe500
	v_add_u32_e32 v128, s3, v146
	s_ashr_i32 s31, s30, 31
	s_lshl_b32 s3, s13, 6
	s_lshl_b64 s[4:5], s[30:31], 8
	s_ashr_i32 s10, s3, 31
	s_add_u32 s4, s3, s4
	v_ashrrev_i32_e32 v205, 31, v204
	s_addc_u32 s5, s10, s5
	v_lshl_add_u64 v[130:131], s[4:5], 0, v[204:205]
	v_readlane_b32 s4, v251, 46
	v_ashrrev_i32_e32 v129, 31, v128
	v_readlane_b32 s5, v251, 47
	s_nop 1
	s_movk_i32 s3, 0x1800
	v_lshl_add_u64 v[128:129], v[128:129], 1, s[4:5]
	v_mad_u64_u32 v[128:129], s[4:5], v130, s3, v[128:129]
	v_mad_i32_i24 v129, v131, s3, v129
	s_nop 1
	s_mov_b32 s4, 0xbfb8aa3b
	s_mov_b32 s5, 0xbfb8aa3b
	v_pk_mul_f32 v[136:137], v[108:109], s[4:5]
	v_pk_mul_f32 v[138:139], v[110:111], s[4:5]
	v_pk_mul_f32 v[132:133], v[124:125], s[4:5]
	v_pk_mul_f32 v[134:135], v[126:127], s[4:5]
	v_exp_f32_e32 v136, v136
	v_exp_f32_e32 v137, v137
	v_exp_f32_e32 v138, v138
	v_exp_f32_e32 v139, v139
	v_exp_f32_e32 v132, v132
	v_exp_f32_e32 v133, v133
	v_exp_f32_e32 v134, v134
	v_exp_f32_e32 v135, v135
	v_pk_add_f32 v[136:137], v[136:137], 1.0 op_sel_hi:[1,0]
	v_pk_add_f32 v[138:139], v[138:139], 1.0 op_sel_hi:[1,0]
	v_pk_add_f32 v[132:133], v[132:133], 1.0 op_sel_hi:[1,0]
	v_pk_add_f32 v[134:135], v[134:135], 1.0 op_sel_hi:[1,0]
	v_rcp_f32_e32 v136, v136
	v_rcp_f32_e32 v137, v137
	v_rcp_f32_e32 v138, v138
	v_rcp_f32_e32 v139, v139
	v_rcp_f32_e32 v132, v132
	v_rcp_f32_e32 v133, v133
	v_rcp_f32_e32 v134, v134
	v_rcp_f32_e32 v135, v135
	v_pk_mul_f32 v[136:137], v[108:109], v[136:137]
	v_pk_mul_f32 v[138:139], v[110:111], v[138:139]
	v_pk_mul_f32 v[132:133], v[124:125], v[132:133]
	v_pk_mul_f32 v[134:135], v[126:127], v[134:135]
	v_cvt_pk_bf16_f32 v132, v132, v133
	v_cvt_pk_bf16_f32 v133, v134, v135
	v_cvt_pk_bf16_f32 v134, v136, v137
	v_cvt_pk_bf16_f32 v135, v138, v139
	global_store_dwordx4 v[128:129], v[132:135], off
	v_pk_mul_f32 v[136:137], v[104:105], s[4:5]
	v_pk_mul_f32 v[138:139], v[106:107], s[4:5]
	v_pk_mul_f32 v[132:133], v[120:121], s[4:5]
	v_pk_mul_f32 v[134:135], v[122:123], s[4:5]
	v_exp_f32_e32 v136, v136
	v_exp_f32_e32 v137, v137
	v_exp_f32_e32 v138, v138
	v_exp_f32_e32 v139, v139
	v_exp_f32_e32 v132, v132
	v_exp_f32_e32 v133, v133
	v_exp_f32_e32 v134, v134
	v_exp_f32_e32 v135, v135
	v_pk_add_f32 v[136:137], v[136:137], 1.0 op_sel_hi:[1,0]
	v_pk_add_f32 v[138:139], v[138:139], 1.0 op_sel_hi:[1,0]
	v_pk_add_f32 v[132:133], v[132:133], 1.0 op_sel_hi:[1,0]
	v_pk_add_f32 v[134:135], v[134:135], 1.0 op_sel_hi:[1,0]
	v_rcp_f32_e32 v136, v136
	v_rcp_f32_e32 v137, v137
	v_rcp_f32_e32 v138, v138
	v_rcp_f32_e32 v139, v139
	v_rcp_f32_e32 v132, v132
	v_rcp_f32_e32 v133, v133
	v_rcp_f32_e32 v134, v134
	v_rcp_f32_e32 v135, v135
	v_pk_mul_f32 v[136:137], v[104:105], v[136:137]
	v_pk_mul_f32 v[138:139], v[106:107], v[138:139]
	v_pk_mul_f32 v[132:133], v[120:121], v[132:133]
	v_pk_mul_f32 v[134:135], v[122:123], v[134:135]
	v_cvt_pk_bf16_f32 v132, v132, v133
	v_cvt_pk_bf16_f32 v133, v134, v135
	v_cvt_pk_bf16_f32 v134, v136, v137
	v_cvt_pk_bf16_f32 v135, v138, v139
	global_store_dwordx4 v[128:129], v[132:135], off offset:256
	v_add_co_u32_e32 v130, vcc, 0x18000, v128
	s_nop 1
	v_addc_co_u32_e32 v131, vcc, 0, v129, vcc
	v_pk_mul_f32 v[136:137], v[100:101], s[4:5]
	v_pk_mul_f32 v[138:139], v[102:103], s[4:5]
	v_pk_mul_f32 v[132:133], v[116:117], s[4:5]
	v_pk_mul_f32 v[134:135], v[118:119], s[4:5]
	v_exp_f32_e32 v136, v136
	v_exp_f32_e32 v137, v137
	v_exp_f32_e32 v138, v138
	v_exp_f32_e32 v139, v139
	v_exp_f32_e32 v132, v132
	v_exp_f32_e32 v133, v133
	v_exp_f32_e32 v134, v134
	v_exp_f32_e32 v135, v135
	v_pk_add_f32 v[136:137], v[136:137], 1.0 op_sel_hi:[1,0]
	v_pk_add_f32 v[138:139], v[138:139], 1.0 op_sel_hi:[1,0]
	v_pk_add_f32 v[132:133], v[132:133], 1.0 op_sel_hi:[1,0]
	v_pk_add_f32 v[134:135], v[134:135], 1.0 op_sel_hi:[1,0]
	v_rcp_f32_e32 v136, v136
	v_rcp_f32_e32 v137, v137
	v_rcp_f32_e32 v138, v138
	v_rcp_f32_e32 v139, v139
	v_rcp_f32_e32 v132, v132
	v_rcp_f32_e32 v133, v133
	v_rcp_f32_e32 v134, v134
	v_rcp_f32_e32 v135, v135
	v_pk_mul_f32 v[136:137], v[100:101], v[136:137]
	v_pk_mul_f32 v[138:139], v[102:103], v[138:139]
	v_pk_mul_f32 v[132:133], v[116:117], v[132:133]
	v_pk_mul_f32 v[134:135], v[118:119], v[134:135]
	v_cvt_pk_bf16_f32 v132, v132, v133
	v_cvt_pk_bf16_f32 v133, v134, v135
	v_cvt_pk_bf16_f32 v134, v136, v137
	v_cvt_pk_bf16_f32 v135, v138, v139
	global_store_dwordx4 v[130:131], v[132:135], off
	v_pk_mul_f32 v[136:137], v[96:97], s[4:5]
	v_pk_mul_f32 v[138:139], v[98:99], s[4:5]
	v_pk_mul_f32 v[132:133], v[112:113], s[4:5]
	v_pk_mul_f32 v[134:135], v[114:115], s[4:5]
	v_exp_f32_e32 v136, v136
	v_exp_f32_e32 v137, v137
	v_exp_f32_e32 v138, v138
	v_exp_f32_e32 v139, v139
	v_exp_f32_e32 v132, v132
	v_exp_f32_e32 v133, v133
	v_exp_f32_e32 v134, v134
	v_exp_f32_e32 v135, v135
	v_pk_add_f32 v[136:137], v[136:137], 1.0 op_sel_hi:[1,0]
	v_pk_add_f32 v[138:139], v[138:139], 1.0 op_sel_hi:[1,0]
	v_pk_add_f32 v[132:133], v[132:133], 1.0 op_sel_hi:[1,0]
	v_pk_add_f32 v[134:135], v[134:135], 1.0 op_sel_hi:[1,0]
	v_rcp_f32_e32 v136, v136
	v_rcp_f32_e32 v137, v137
	v_rcp_f32_e32 v138, v138
	v_rcp_f32_e32 v139, v139
	v_rcp_f32_e32 v132, v132
	v_rcp_f32_e32 v133, v133
	v_rcp_f32_e32 v134, v134
	v_rcp_f32_e32 v135, v135
	v_pk_mul_f32 v[136:137], v[96:97], v[136:137]
	v_pk_mul_f32 v[138:139], v[98:99], v[138:139]
	v_pk_mul_f32 v[132:133], v[112:113], v[132:133]
	v_pk_mul_f32 v[134:135], v[114:115], v[134:135]
	v_cvt_pk_bf16_f32 v132, v132, v133
	v_cvt_pk_bf16_f32 v133, v134, v135
	v_cvt_pk_bf16_f32 v134, v136, v137
	v_cvt_pk_bf16_f32 v135, v138, v139
; __device__ __forceinline__ float sigm_f(float x) { return __builtin_amdgcn_rcpf(1.f + __builtin_amdgcn_exp2f(-1.4426950408889634f * x)); }
; __device__ __forceinline__ float silu_f(float x) { return x * sigm_f(x); }
;     template <int ACT>
;     __device__ __forceinline__ void plain(const f32x4 (&acc)[2][2][4][2], int pm, int wr, int wc, int fr, int fq, bf16_t* dst, int ld, int col0) const {
;     ...
;         for (int ai = 0; ai < 2; ++ai)
; #pragma unroll
;             for (int m = 0; m < 4; ++m) {
;                 const size_t row = (size_t)pm * 256 + ai * 128 + wr * 64 + m * 16 + fr;
; #pragma unroll
;                 for (int bj = 0; bj < 2; ++bj) {
;                     f32x4 v0 = acc[ai][bj][m][0], v1 = acc[ai][bj][m][1];
;                     if (ACT == 1) { for (int j = 0; j < 4; ++j) { v0[j] = silu_f(v0[j]); v1[j] = silu_f(v1[j]); } }
;                     if (ACT == 2) { v0 = v0 + b[bj][0]; v1 = v1 + b[bj][1]; for (int j = 0; j < 4; ++j) { v0[j] = sigm_f(v0[j]); v1[j] = sigm_f(v1[j]); } }
;                     if (ACT == 0) store8(dst + row * ld + colw + bj * 128, v0, v1); else store8_safe(dst + row * ld + colw + bj * 128, v0, v1);
;                 }
;                 __builtin_amdgcn_sched_barrier(0);
;             }
	global_store_dwordx4 v[130:131], v[132:135], off offset:256
	v_add_co_u32_e32 v130, vcc, 0x30000, v128
	s_nop 1
	v_addc_co_u32_e32 v131, vcc, 0, v129, vcc
	v_pk_mul_f32 v[136:137], v[76:77], s[4:5]
	v_pk_mul_f32 v[138:139], v[78:79], s[4:5]
	v_pk_mul_f32 v[132:133], v[92:93], s[4:5]
	v_pk_mul_f32 v[134:135], v[94:95], s[4:5]
	v_exp_f32_e32 v136, v136
	v_exp_f32_e32 v137, v137
	v_exp_f32_e32 v138, v138
	v_exp_f32_e32 v139, v139
	v_exp_f32_e32 v132, v132
	v_exp_f32_e32 v133, v133
	v_exp_f32_e32 v134, v134
	v_exp_f32_e32 v135, v135
	v_pk_add_f32 v[136:137], v[136:137], 1.0 op_sel_hi:[1,0]
	v_pk_add_f32 v[138:139], v[138:139], 1.0 op_sel_hi:[1,0]
	v_pk_add_f32 v[132:133], v[132:133], 1.0 op_sel_hi:[1,0]
	v_pk_add_f32 v[134:135], v[134:135], 1.0 op_sel_hi:[1,0]
	v_rcp_f32_e32 v136, v136
	v_rcp_f32_e32 v137, v137
	v_rcp_f32_e32 v138, v138
	v_rcp_f32_e32 v139, v139
	v_rcp_f32_e32 v132, v132
	v_rcp_f32_e32 v133, v133
	v_rcp_f32_e32 v134, v134
	v_rcp_f32_e32 v135, v135
	v_pk_mul_f32 v[136:137], v[76:77], v[136:137]
	v_pk_mul_f32 v[138:139], v[78:79], v[138:139]
	v_pk_mul_f32 v[132:133], v[92:93], v[132:133]
	v_pk_mul_f32 v[134:135], v[94:95], v[134:135]
	v_cvt_pk_bf16_f32 v132, v132, v133
	v_cvt_pk_bf16_f32 v133, v134, v135
	v_cvt_pk_bf16_f32 v134, v136, v137
	v_cvt_pk_bf16_f32 v135, v138, v139
	global_store_dwordx4 v[130:131], v[132:135], off
	v_pk_mul_f32 v[136:137], v[72:73], s[4:5]
	v_pk_mul_f32 v[138:139], v[74:75], s[4:5]
	v_pk_mul_f32 v[132:133], v[88:89], s[4:5]
	v_pk_mul_f32 v[134:135], v[90:91], s[4:5]
	v_exp_f32_e32 v136, v136
	v_exp_f32_e32 v137, v137
	v_exp_f32_e32 v138, v138
	v_exp_f32_e32 v139, v139
	v_exp_f32_e32 v132, v132
	v_exp_f32_e32 v133, v133
	v_exp_f32_e32 v134, v134
	v_exp_f32_e32 v135, v135
	v_pk_add_f32 v[136:137], v[136:137], 1.0 op_sel_hi:[1,0]
	v_pk_add_f32 v[138:139], v[138:139], 1.0 op_sel_hi:[1,0]
	v_pk_add_f32 v[132:133], v[132:133], 1.0 op_sel_hi:[1,0]
	v_pk_add_f32 v[134:135], v[134:135], 1.0 op_sel_hi:[1,0]
	v_rcp_f32_e32 v136, v136
	v_rcp_f32_e32 v137, v137
	v_rcp_f32_e32 v138, v138
	v_rcp_f32_e32 v139, v139
	v_rcp_f32_e32 v132, v132
	v_rcp_f32_e32 v133, v133
	v_rcp_f32_e32 v134, v134
	v_rcp_f32_e32 v135, v135
	v_pk_mul_f32 v[136:137], v[72:73], v[136:137]
	v_pk_mul_f32 v[138:139], v[74:75], v[138:139]
	v_pk_mul_f32 v[132:133], v[88:89], v[132:133]
	v_pk_mul_f32 v[134:135], v[90:91], v[134:135]
	v_cvt_pk_bf16_f32 v132, v132, v133
	v_cvt_pk_bf16_f32 v133, v134, v135
	v_cvt_pk_bf16_f32 v134, v136, v137
	v_cvt_pk_bf16_f32 v135, v138, v139
	global_store_dwordx4 v[130:131], v[132:135], off offset:256
	v_add_co_u32_e32 v130, vcc, 0x48000, v128
	s_nop 1
	v_addc_co_u32_e32 v131, vcc, 0, v129, vcc
	v_pk_mul_f32 v[136:137], v[68:69], s[4:5]
	v_pk_mul_f32 v[138:139], v[70:71], s[4:5]
	v_pk_mul_f32 v[132:133], v[84:85], s[4:5]
	v_pk_mul_f32 v[134:135], v[86:87], s[4:5]
	v_exp_f32_e32 v136, v136
	v_exp_f32_e32 v137, v137
	v_exp_f32_e32 v138, v138
	v_exp_f32_e32 v139, v139
	v_exp_f32_e32 v132, v132
	v_exp_f32_e32 v133, v133
	v_exp_f32_e32 v134, v134
	v_exp_f32_e32 v135, v135
	v_pk_add_f32 v[136:137], v[136:137], 1.0 op_sel_hi:[1,0]
	v_pk_add_f32 v[138:139], v[138:139], 1.0 op_sel_hi:[1,0]
	v_pk_add_f32 v[132:133], v[132:133], 1.0 op_sel_hi:[1,0]
	v_pk_add_f32 v[134:135], v[134:135], 1.0 op_sel_hi:[1,0]
	v_rcp_f32_e32 v136, v136
	v_rcp_f32_e32 v137, v137
	v_rcp_f32_e32 v138, v138
	v_rcp_f32_e32 v139, v139
	v_rcp_f32_e32 v132, v132
	v_rcp_f32_e32 v133, v133
	v_rcp_f32_e32 v134, v134
	v_rcp_f32_e32 v135, v135
	v_pk_mul_f32 v[136:137], v[68:69], v[136:137]
	v_pk_mul_f32 v[138:139], v[70:71], v[138:139]
	v_pk_mul_f32 v[132:133], v[84:85], v[132:133]
	v_pk_mul_f32 v[134:135], v[86:87], v[134:135]
	v_cvt_pk_bf16_f32 v132, v132, v133
	v_cvt_pk_bf16_f32 v133, v134, v135
	v_cvt_pk_bf16_f32 v134, v136, v137
	v_cvt_pk_bf16_f32 v135, v138, v139
	global_store_dwordx4 v[130:131], v[132:135], off
	v_pk_mul_f32 v[136:137], v[64:65], s[4:5]
	v_pk_mul_f32 v[138:139], v[66:67], s[4:5]
	v_pk_mul_f32 v[132:133], v[80:81], s[4:5]
	v_pk_mul_f32 v[134:135], v[82:83], s[4:5]
	v_exp_f32_e32 v136, v136
	v_exp_f32_e32 v137, v137
	v_exp_f32_e32 v138, v138
	v_exp_f32_e32 v139, v139
	v_exp_f32_e32 v132, v132
	v_exp_f32_e32 v133, v133
	v_exp_f32_e32 v134, v134
	v_exp_f32_e32 v135, v135
	v_pk_add_f32 v[136:137], v[136:137], 1.0 op_sel_hi:[1,0]
	v_pk_add_f32 v[138:139], v[138:139], 1.0 op_sel_hi:[1,0]
	v_pk_add_f32 v[132:133], v[132:133], 1.0 op_sel_hi:[1,0]
	v_pk_add_f32 v[134:135], v[134:135], 1.0 op_sel_hi:[1,0]
	v_rcp_f32_e32 v136, v136
	v_rcp_f32_e32 v137, v137
	v_rcp_f32_e32 v138, v138
	v_rcp_f32_e32 v139, v139
	v_rcp_f32_e32 v132, v132
	v_rcp_f32_e32 v133, v133
	v_rcp_f32_e32 v134, v134
	v_rcp_f32_e32 v135, v135
	v_pk_mul_f32 v[136:137], v[64:65], v[136:137]
	v_pk_mul_f32 v[138:139], v[66:67], v[138:139]
	v_pk_mul_f32 v[132:133], v[80:81], v[132:133]
	v_pk_mul_f32 v[134:135], v[82:83], v[134:135]
	v_cvt_pk_bf16_f32 v132, v132, v133
	v_cvt_pk_bf16_f32 v133, v134, v135
	v_cvt_pk_bf16_f32 v134, v136, v137
	v_cvt_pk_bf16_f32 v135, v138, v139
	global_store_dwordx4 v[130:131], v[132:135], off offset:256
	v_add_co_u32_e32 v130, vcc, 0xc0000, v128
	s_nop 1
	v_addc_co_u32_e32 v131, vcc, 0, v129, vcc
	v_pk_mul_f32 v[136:137], v[44:45], s[4:5]
	v_pk_mul_f32 v[138:139], v[46:47], s[4:5]
	v_pk_mul_f32 v[132:133], v[60:61], s[4:5]
	v_pk_mul_f32 v[134:135], v[62:63], s[4:5]
	v_exp_f32_e32 v136, v136
	v_exp_f32_e32 v137, v137
	v_exp_f32_e32 v138, v138
	v_exp_f32_e32 v139, v139
	v_exp_f32_e32 v132, v132
	v_exp_f32_e32 v133, v133
	v_exp_f32_e32 v134, v134
	v_exp_f32_e32 v135, v135
	v_pk_add_f32 v[136:137], v[136:137], 1.0 op_sel_hi:[1,0]
; __device__ __forceinline__ float sigm_f(float x) { return __builtin_amdgcn_rcpf(1.f + __builtin_amdgcn_exp2f(-1.4426950408889634f * x)); }
; __device__ __forceinline__ float silu_f(float x) { return x * sigm_f(x); }
;     template <int ACT>
;     __device__ __forceinline__ void plain(const f32x4 (&acc)[2][2][4][2], int pm, int wr, int wc, int fr, int fq, bf16_t* dst, int ld, int col0) const {
;     ...
;         for (int ai = 0; ai < 2; ++ai)
; #pragma unroll
;             for (int m = 0; m < 4; ++m) {
;                 const size_t row = (size_t)pm * 256 + ai * 128 + wr * 64 + m * 16 + fr;
; #pragma unroll
;                 for (int bj = 0; bj < 2; ++bj) {
;                     f32x4 v0 = acc[ai][bj][m][0], v1 = acc[ai][bj][m][1];
;                     if (ACT == 1) { for (int j = 0; j < 4; ++j) { v0[j] = silu_f(v0[j]); v1[j] = silu_f(v1[j]); } }
;                     if (ACT == 2) { v0 = v0 + b[bj][0]; v1 = v1 + b[bj][1]; for (int j = 0; j < 4; ++j) { v0[j] = sigm_f(v0[j]); v1[j] = sigm_f(v1[j]); } }
;                     if (ACT == 0) store8(dst + row * ld + colw + bj * 128, v0, v1); else store8_safe(dst + row * ld + colw + bj * 128, v0, v1);
;                 }
;                 __builtin_amdgcn_sched_barrier(0);
;             }
	v_pk_add_f32 v[138:139], v[138:139], 1.0 op_sel_hi:[1,0]
	v_pk_add_f32 v[132:133], v[132:133], 1.0 op_sel_hi:[1,0]
	v_pk_add_f32 v[134:135], v[134:135], 1.0 op_sel_hi:[1,0]
	v_rcp_f32_e32 v136, v136
	v_rcp_f32_e32 v137, v137
	v_rcp_f32_e32 v138, v138
	v_rcp_f32_e32 v139, v139
	v_rcp_f32_e32 v132, v132
	v_rcp_f32_e32 v133, v133
	v_rcp_f32_e32 v134, v134
	v_rcp_f32_e32 v135, v135
	v_pk_mul_f32 v[136:137], v[44:45], v[136:137]
	v_pk_mul_f32 v[138:139], v[46:47], v[138:139]
	v_pk_mul_f32 v[132:133], v[60:61], v[132:133]
	v_pk_mul_f32 v[134:135], v[62:63], v[134:135]
	v_cvt_pk_bf16_f32 v132, v132, v133
	v_cvt_pk_bf16_f32 v133, v134, v135
	v_cvt_pk_bf16_f32 v134, v136, v137
	v_cvt_pk_bf16_f32 v135, v138, v139
	global_store_dwordx4 v[130:131], v[132:135], off
	v_pk_mul_f32 v[136:137], v[40:41], s[4:5]
	v_pk_mul_f32 v[138:139], v[42:43], s[4:5]
	v_pk_mul_f32 v[132:133], v[56:57], s[4:5]
	v_pk_mul_f32 v[134:135], v[58:59], s[4:5]
	v_exp_f32_e32 v136, v136
	v_exp_f32_e32 v137, v137
	v_exp_f32_e32 v138, v138
	v_exp_f32_e32 v139, v139
	v_exp_f32_e32 v132, v132
	v_exp_f32_e32 v133, v133
	v_exp_f32_e32 v134, v134
	v_exp_f32_e32 v135, v135
	v_pk_add_f32 v[136:137], v[136:137], 1.0 op_sel_hi:[1,0]
	v_pk_add_f32 v[138:139], v[138:139], 1.0 op_sel_hi:[1,0]
	v_pk_add_f32 v[132:133], v[132:133], 1.0 op_sel_hi:[1,0]
	v_pk_add_f32 v[134:135], v[134:135], 1.0 op_sel_hi:[1,0]
	v_rcp_f32_e32 v136, v136
	v_rcp_f32_e32 v137, v137
	v_rcp_f32_e32 v138, v138
	v_rcp_f32_e32 v139, v139
	v_rcp_f32_e32 v132, v132
	v_rcp_f32_e32 v133, v133
	v_rcp_f32_e32 v134, v134
	v_rcp_f32_e32 v135, v135
	v_pk_mul_f32 v[136:137], v[40:41], v[136:137]
	v_pk_mul_f32 v[138:139], v[42:43], v[138:139]
	v_pk_mul_f32 v[132:133], v[56:57], v[132:133]
	v_pk_mul_f32 v[134:135], v[58:59], v[134:135]
	v_cvt_pk_bf16_f32 v132, v132, v133
	v_cvt_pk_bf16_f32 v133, v134, v135
	v_cvt_pk_bf16_f32 v134, v136, v137
	v_cvt_pk_bf16_f32 v135, v138, v139
	global_store_dwordx4 v[130:131], v[132:135], off offset:256
	v_add_co_u32_e32 v130, vcc, 0xd8000, v128
	s_nop 1
	v_addc_co_u32_e32 v131, vcc, 0, v129, vcc
	v_pk_mul_f32 v[136:137], v[36:37], s[4:5]
	v_pk_mul_f32 v[138:139], v[38:39], s[4:5]
	v_pk_mul_f32 v[132:133], v[52:53], s[4:5]
	v_pk_mul_f32 v[134:135], v[54:55], s[4:5]
	v_exp_f32_e32 v136, v136
	v_exp_f32_e32 v137, v137
	v_exp_f32_e32 v138, v138
	v_exp_f32_e32 v139, v139
	v_exp_f32_e32 v132, v132
	v_exp_f32_e32 v133, v133
	v_exp_f32_e32 v134, v134
	v_exp_f32_e32 v135, v135
	v_pk_add_f32 v[136:137], v[136:137], 1.0 op_sel_hi:[1,0]
	v_pk_add_f32 v[138:139], v[138:139], 1.0 op_sel_hi:[1,0]
	v_pk_add_f32 v[132:133], v[132:133], 1.0 op_sel_hi:[1,0]
	v_pk_add_f32 v[134:135], v[134:135], 1.0 op_sel_hi:[1,0]
	v_rcp_f32_e32 v136, v136
	v_rcp_f32_e32 v137, v137
	v_rcp_f32_e32 v138, v138
	v_rcp_f32_e32 v139, v139
	v_rcp_f32_e32 v132, v132
	v_rcp_f32_e32 v133, v133
	v_rcp_f32_e32 v134, v134
	v_rcp_f32_e32 v135, v135
	v_pk_mul_f32 v[136:137], v[36:37], v[136:137]
	v_pk_mul_f32 v[138:139], v[38:39], v[138:139]
	v_pk_mul_f32 v[132:133], v[52:53], v[132:133]
	v_pk_mul_f32 v[134:135], v[54:55], v[134:135]
	v_cvt_pk_bf16_f32 v132, v132, v133
	v_cvt_pk_bf16_f32 v133, v134, v135
	v_cvt_pk_bf16_f32 v134, v136, v137
	v_cvt_pk_bf16_f32 v135, v138, v139
	global_store_dwordx4 v[130:131], v[132:135], off
	v_pk_mul_f32 v[136:137], v[32:33], s[4:5]
	v_pk_mul_f32 v[138:139], v[34:35], s[4:5]
	v_pk_mul_f32 v[132:133], v[48:49], s[4:5]
	v_pk_mul_f32 v[134:135], v[50:51], s[4:5]
	v_exp_f32_e32 v136, v136
	v_exp_f32_e32 v137, v137
	v_exp_f32_e32 v138, v138
	v_exp_f32_e32 v139, v139
	v_exp_f32_e32 v132, v132
	v_exp_f32_e32 v133, v133
	v_exp_f32_e32 v134, v134
	v_exp_f32_e32 v135, v135
	v_pk_add_f32 v[136:137], v[136:137], 1.0 op_sel_hi:[1,0]
	v_pk_add_f32 v[138:139], v[138:139], 1.0 op_sel_hi:[1,0]
	v_pk_add_f32 v[132:133], v[132:133], 1.0 op_sel_hi:[1,0]
	v_pk_add_f32 v[134:135], v[134:135], 1.0 op_sel_hi:[1,0]
	v_rcp_f32_e32 v136, v136
	v_rcp_f32_e32 v137, v137
	v_rcp_f32_e32 v138, v138
	v_rcp_f32_e32 v139, v139
	v_rcp_f32_e32 v132, v132
	v_rcp_f32_e32 v133, v133
	v_rcp_f32_e32 v134, v134
	v_rcp_f32_e32 v135, v135
	v_pk_mul_f32 v[136:137], v[32:33], v[136:137]
	v_pk_mul_f32 v[138:139], v[34:35], v[138:139]
	v_pk_mul_f32 v[132:133], v[48:49], v[132:133]
	v_pk_mul_f32 v[134:135], v[50:51], v[134:135]
	v_cvt_pk_bf16_f32 v132, v132, v133
	v_cvt_pk_bf16_f32 v133, v134, v135
	v_cvt_pk_bf16_f32 v134, v136, v137
	v_cvt_pk_bf16_f32 v135, v138, v139
	global_store_dwordx4 v[130:131], v[132:135], off offset:256
	v_add_co_u32_e32 v130, vcc, 0xf0000, v128
	s_nop 1
	v_addc_co_u32_e32 v131, vcc, 0, v129, vcc
	v_pk_mul_f32 v[136:137], v[12:13], s[4:5]
	v_pk_mul_f32 v[138:139], v[14:15], s[4:5]
	v_pk_mul_f32 v[132:133], v[28:29], s[4:5]
	v_pk_mul_f32 v[134:135], v[30:31], s[4:5]
; __device__ __forceinline__ float sigm_f(float x) { return __builtin_amdgcn_rcpf(1.f + __builtin_amdgcn_exp2f(-1.4426950408889634f * x)); }
; __device__ __forceinline__ float silu_f(float x) { return x * sigm_f(x); }
;     template <int ACT>
;     __device__ __forceinline__ void plain(const f32x4 (&acc)[2][2][4][2], int pm, int wr, int wc, int fr, int fq, bf16_t* dst, int ld, int col0) const {
;     ...
;         for (int ai = 0; ai < 2; ++ai)
; #pragma unroll
;             for (int m = 0; m < 4; ++m) {
;                 const size_t row = (size_t)pm * 256 + ai * 128 + wr * 64 + m * 16 + fr;
; #pragma unroll
;                 for (int bj = 0; bj < 2; ++bj) {
;                     f32x4 v0 = acc[ai][bj][m][0], v1 = acc[ai][bj][m][1];
;                     if (ACT == 1) { for (int j = 0; j < 4; ++j) { v0[j] = silu_f(v0[j]); v1[j] = silu_f(v1[j]); } }
;                     if (ACT == 2) { v0 = v0 + b[bj][0]; v1 = v1 + b[bj][1]; for (int j = 0; j < 4; ++j) { v0[j] = sigm_f(v0[j]); v1[j] = sigm_f(v1[j]); } }
;                     if (ACT == 0) store8(dst + row * ld + colw + bj * 128, v0, v1); else store8_safe(dst + row * ld + colw + bj * 128, v0, v1);
;                 }
;                 __builtin_amdgcn_sched_barrier(0);
;             }
	v_exp_f32_e32 v136, v136
	v_exp_f32_e32 v137, v137
	v_exp_f32_e32 v138, v138
	v_exp_f32_e32 v139, v139
	v_exp_f32_e32 v132, v132
	v_exp_f32_e32 v133, v133
	v_exp_f32_e32 v134, v134
	v_exp_f32_e32 v135, v135
	v_pk_add_f32 v[136:137], v[136:137], 1.0 op_sel_hi:[1,0]
	v_pk_add_f32 v[138:139], v[138:139], 1.0 op_sel_hi:[1,0]
	v_pk_add_f32 v[132:133], v[132:133], 1.0 op_sel_hi:[1,0]
	v_pk_add_f32 v[134:135], v[134:135], 1.0 op_sel_hi:[1,0]
	v_rcp_f32_e32 v136, v136
	v_rcp_f32_e32 v137, v137
	v_rcp_f32_e32 v138, v138
	v_rcp_f32_e32 v139, v139
	v_rcp_f32_e32 v132, v132
	v_rcp_f32_e32 v133, v133
	v_rcp_f32_e32 v134, v134
	v_rcp_f32_e32 v135, v135
	v_pk_mul_f32 v[136:137], v[12:13], v[136:137]
	v_pk_mul_f32 v[138:139], v[14:15], v[138:139]
	v_pk_mul_f32 v[132:133], v[28:29], v[132:133]
	v_pk_mul_f32 v[134:135], v[30:31], v[134:135]
	v_cvt_pk_bf16_f32 v132, v132, v133
	v_cvt_pk_bf16_f32 v133, v134, v135
	v_cvt_pk_bf16_f32 v134, v136, v137
	v_cvt_pk_bf16_f32 v135, v138, v139
	global_store_dwordx4 v[130:131], v[132:135], off
	v_pk_mul_f32 v[136:137], v[8:9], s[4:5]
	v_pk_mul_f32 v[138:139], v[10:11], s[4:5]
	v_pk_mul_f32 v[132:133], v[24:25], s[4:5]
	v_pk_mul_f32 v[134:135], v[26:27], s[4:5]
	v_exp_f32_e32 v136, v136
	v_exp_f32_e32 v137, v137
	v_exp_f32_e32 v138, v138
	v_exp_f32_e32 v139, v139
	v_exp_f32_e32 v132, v132
	v_exp_f32_e32 v133, v133
	v_exp_f32_e32 v134, v134
	v_exp_f32_e32 v135, v135
	v_pk_add_f32 v[136:137], v[136:137], 1.0 op_sel_hi:[1,0]
	v_pk_add_f32 v[138:139], v[138:139], 1.0 op_sel_hi:[1,0]
	v_pk_add_f32 v[132:133], v[132:133], 1.0 op_sel_hi:[1,0]
	v_pk_add_f32 v[134:135], v[134:135], 1.0 op_sel_hi:[1,0]
	v_rcp_f32_e32 v136, v136
	v_rcp_f32_e32 v137, v137
	v_rcp_f32_e32 v138, v138
	v_rcp_f32_e32 v139, v139
	v_rcp_f32_e32 v132, v132
	v_rcp_f32_e32 v133, v133
	v_rcp_f32_e32 v134, v134
	v_rcp_f32_e32 v135, v135
	v_pk_mul_f32 v[136:137], v[8:9], v[136:137]
	v_pk_mul_f32 v[138:139], v[10:11], v[138:139]
	v_pk_mul_f32 v[132:133], v[24:25], v[132:133]
	v_pk_mul_f32 v[134:135], v[26:27], v[134:135]
	v_cvt_pk_bf16_f32 v132, v132, v133
	v_cvt_pk_bf16_f32 v133, v134, v135
	v_cvt_pk_bf16_f32 v134, v136, v137
	v_cvt_pk_bf16_f32 v135, v138, v139
	global_store_dwordx4 v[130:131], v[132:135], off offset:256
	v_add_co_u32_e32 v130, vcc, 0x108000, v128
	s_nop 1
	v_addc_co_u32_e32 v131, vcc, 0, v129, vcc
	v_pk_mul_f32 v[136:137], v[4:5], s[4:5]
	v_pk_mul_f32 v[138:139], v[6:7], s[4:5]
	v_pk_mul_f32 v[132:133], v[20:21], s[4:5]
	v_pk_mul_f32 v[134:135], v[22:23], s[4:5]
	v_exp_f32_e32 v136, v136
	v_exp_f32_e32 v137, v137
	v_exp_f32_e32 v138, v138
	v_exp_f32_e32 v139, v139
	v_exp_f32_e32 v132, v132
	v_exp_f32_e32 v133, v133
	v_exp_f32_e32 v134, v134
	v_exp_f32_e32 v135, v135
	v_pk_add_f32 v[136:137], v[136:137], 1.0 op_sel_hi:[1,0]
	v_pk_add_f32 v[138:139], v[138:139], 1.0 op_sel_hi:[1,0]
	v_pk_add_f32 v[132:133], v[132:133], 1.0 op_sel_hi:[1,0]
	v_pk_add_f32 v[134:135], v[134:135], 1.0 op_sel_hi:[1,0]
	v_rcp_f32_e32 v136, v136
	v_rcp_f32_e32 v137, v137
	v_rcp_f32_e32 v138, v138
	v_rcp_f32_e32 v139, v139
	v_rcp_f32_e32 v132, v132
	v_rcp_f32_e32 v133, v133
	v_rcp_f32_e32 v134, v134
	v_rcp_f32_e32 v135, v135
	v_pk_mul_f32 v[136:137], v[4:5], v[136:137]
	v_pk_mul_f32 v[138:139], v[6:7], v[138:139]
	v_pk_mul_f32 v[132:133], v[20:21], v[132:133]
	v_pk_mul_f32 v[134:135], v[22:23], v[134:135]
	v_cvt_pk_bf16_f32 v132, v132, v133
	v_cvt_pk_bf16_f32 v133, v134, v135
	v_cvt_pk_bf16_f32 v134, v136, v137
	v_cvt_pk_bf16_f32 v135, v138, v139
	global_store_dwordx4 v[130:131], v[132:135], off
	v_pk_mul_f32 v[136:137], v[0:1], s[4:5]
	v_pk_mul_f32 v[138:139], v[2:3], s[4:5]
	v_pk_mul_f32 v[132:133], v[16:17], s[4:5]
	v_pk_mul_f32 v[134:135], v[18:19], s[4:5]
	v_exp_f32_e32 v136, v136
	v_exp_f32_e32 v137, v137
	v_exp_f32_e32 v138, v138
	v_exp_f32_e32 v139, v139
	v_exp_f32_e32 v132, v132
	v_exp_f32_e32 v133, v133
	v_exp_f32_e32 v134, v134
	v_exp_f32_e32 v135, v135
	v_pk_add_f32 v[136:137], v[136:137], 1.0 op_sel_hi:[1,0]
	v_pk_add_f32 v[138:139], v[138:139], 1.0 op_sel_hi:[1,0]
	v_pk_add_f32 v[132:133], v[132:133], 1.0 op_sel_hi:[1,0]
	v_pk_add_f32 v[134:135], v[134:135], 1.0 op_sel_hi:[1,0]
	v_rcp_f32_e32 v136, v136
	v_rcp_f32_e32 v137, v137
	v_rcp_f32_e32 v138, v138
	v_rcp_f32_e32 v139, v139
	v_rcp_f32_e32 v132, v132
	v_rcp_f32_e32 v133, v133
	v_rcp_f32_e32 v134, v134
	v_rcp_f32_e32 v135, v135
	v_pk_mul_f32 v[136:137], v[0:1], v[136:137]
	v_pk_mul_f32 v[138:139], v[2:3], v[138:139]
	v_pk_mul_f32 v[132:133], v[16:17], v[132:133]
	v_pk_mul_f32 v[134:135], v[18:19], v[134:135]
	v_cvt_pk_bf16_f32 v132, v132, v133
	v_cvt_pk_bf16_f32 v133, v134, v135
	v_cvt_pk_bf16_f32 v134, v136, v137
	v_cvt_pk_bf16_f32 v135, v138, v139
	global_store_dwordx4 v[130:131], v[132:135], off offset:256
